# speedup vs baseline: 1.0252x; 1.0064x over previous
; template <int DQK, int MODE> ...
;     ...
;   auto step = [&](TRegs& R, int it) -> bool {
;     const int j = jstart + dir * it;
;     const int st = it & 1;
;     lstore(R, st);
;     if (MODE == 2) {
;       int alive = (carry != 0.f) ? 1 : 0;
;       if (!__syncthreads_or(alive)) return false;
;     } else {
;       __syncthreads();
;     }
;     if (it + 2 < ntile) gload(R, j + 2 * dir);
;     __builtin_amdgcn_sched_barrier(0);
;     if (active && j <= hiw && j >= low) {
;       const u16* Ks = lds + st * STG;
;       const u16* Vs = Ks + KT;
;       f32x16 S[2];
;       const bool far = (MODE == 1) && ((qpos0 + 32 * w) - (j * 64 + 63) >= 256);
;       const float cinit = (MODE != 2) ? (-m_run + (far ? btab[512] : 0.f)) : 0.f;
;       {
;         bf16x8 kf[2][NKK];
; #pragma unroll
;         for (int ku = 0; ku < 2; ++ku)
; #pragma unroll
;           for (int kk = 0; kk < NKK; ++kk)
;             kf[ku][kk] = *(const bf16x8*)(Ks + (ku * 32 + ql) * KST + kk * 16 + hh * 8);
;         __builtin_amdgcn_sched_barrier(0);
; #pragma unroll
;         for (int ku = 0; ku < 2; ++ku)
; #pragma unroll
;           for (int r = 0; r < 16; ++r) S[ku][r] = cinit;
; #pragma unroll
;         for (int kk = 0; kk < NKK; ++kk)
; #pragma unroll
;           for (int ku = 0; ku < 2; ++ku)
;             S[ku] = __builtin_amdgcn_mfma_f32_32x32x16_bf16(kf[ku][kk], qf[kk], S[ku], 0, 0, 0);
;       }
.LBB0_990:
	v_add_u32_e32 v220, s4, v171
	v_add_u32_e32 v220, 0xfc000080, v220
	v_add_u32_e32 v222, s4, v173
	v_mad_i64_i32 v[220:221], s[6:7], v220, s85, v[178:179]
	v_add_u32_e32 v222, 0xfc000080, v222
	v_mad_i64_i32 v[222:223], s[6:7], v222, s85, v[180:181]
	v_add_u32_e32 v224, s4, v175
	v_add_u32_e32 v224, 0xfc000080, v224
	v_mad_i64_i32 v[224:225], s[6:7], v224, s85, v[182:183]
	v_lshl_add_u64 v[244:245], v[188:189], 0, s[10:11]
	v_add_co_u32_e32 v244, vcc, 0x4000, v244
	s_nop 1
	v_addc_co_u32_e32 v245, vcc, -2, v245, vcc
	v_lshl_add_u64 v[248:249], v[190:191], 0, s[10:11]
	v_add_co_u32_e32 v248, vcc, 0x4000, v248
	s_nop 1
	v_addc_co_u32_e32 v249, vcc, -2, v249, vcc
	s_add_i32 s6, s12, s3
	s_add_i32 s7, s6, 0xffeffffd
	v_cmp_le_i32_e32 vcc, s7, v199
	s_and_b64 s[16:17], s[14:15], vcc
	v_cmp_ge_u32_e32 vcc, s7, v200
	s_and_b64 s[18:19], s[16:17], vcc
	s_add_i32 s5, s3, -1
	s_cmp_gt_i32 s5, s2
	s_waitcnt lgkmcnt(0)
	s_barrier
	s_cbranch_scc1 .LBB0_992
	global_load_dwordx4 v[106:109], v[220:221], off
	global_load_dwordx4 v[110:113], v[222:223], off
	global_load_dwordx4 v[114:117], v[224:225], off
	global_load_dwordx4 v[118:121], v[244:245], off
	global_load_dwordx4 v[130:133], v[248:249], off
.LBB0_992:
	s_and_saveexec_b64 s[16:17], s[18:19]
	s_cbranch_execz .Lmy_ia0_a
	ds_read_b128 v[4:7], v185
	ds_read_b128 v[8:11], v185 offset:32
	ds_read_b128 v[12:15], v185 offset:64
	ds_read_b128 v[146:149], v185 offset:96
	ds_read_b128 v[150:153], v185 offset:128
	ds_read_b128 v[154:157], v185 offset:160
	ds_read_b128 v[158:161], v185 offset:6656
	ds_read_b128 v[162:165], v185 offset:6688
	ds_read_b128 v[204:207], v185 offset:6720
	ds_read_b128 v[208:211], v185 offset:6752
	ds_read_b128 v[212:215], v185 offset:6784
	ds_read_b128 v[216:219], v185 offset:6816
	s_setprio 1
	s_waitcnt lgkmcnt(11)
	v_mfma_f32_32x32x16_bf16 v[66:81], v[4:7], v[86:89], v[228:243]
	v_add_u32_e32 v4, 0x3000, v187
	s_waitcnt lgkmcnt(5)
	v_mfma_f32_32x32x16_bf16 v[50:65], v[158:161], v[86:89], v[228:243]
	s_cmp_gt_i32 s5, s2
	s_cbranch_scc1 .Lmy_w1_nl
	v_add_u32_e32 v226, 0x8e00, v184
	s_waitcnt vmcnt(9)
	ds_write_b128 v201, v[122:125] offset:23040
	s_waitcnt vmcnt(8)
	ds_write_b128 v202, v[126:129] offset:23040
	s_waitcnt vmcnt(7)
	ds_write_b128 v203, v[134:137] offset:23040
	s_waitcnt vmcnt(6)
	ds_write2_b64 v226, v[138:139], v[140:141] offset1:1
	v_add_u32_e32 v226, 0x8e00, v186
	s_waitcnt vmcnt(5)
	ds_write2_b64 v226, v[142:143], v[144:145] offset1:1
	s_branch .Lmy_w1_dn

; template <int DQK, int MODE> ...
;     ...
;         for (int kk = 0; kk < NKK; ++kk)
; #pragma unroll
;           for (int ku = 0; ku < 2; ++ku)
;             S[ku] = __builtin_amdgcn_mfma_f32_32x32x16_bf16(kf[ku][kk], qf[kk], S[ku], 0, 0, 0);
;       }
;       u32x4 vf[2][4];
;       if (MODE != 2) {
; #pragma unroll
;         for (int du = 0; du < 2; ++du)
; #pragma unroll
;           for (int s4 = 0; s4 < 4; ++s4) {
;             const u16* vp = Vs + (du * 32 + ql) * VST + 16 * s4 + 4 * hh;
;             u32x2 a = *(const u32x2*)vp;
;             u32x2 b = *(const u32x2*)(vp + 8);
;             vf[du][s4] = (u32x4){a.x, a.y, b.x, b.y};
;           }
;         __builtin_amdgcn_sched_barrier(0);
;       }
;       bf16x8 pf[4];
;       if (MODE != 2) {
;         if (MODE == 1 && !far) {
;           const bool noclip = ((qpos0 + 32 * w + 31) - j * 64 <= 256) && ((qpos0 + 32 * w) - (j * 64 + 63) >= -256);
;           if (noclip) {
;             const float* bt = btab + 256 + qpos - j * 64;
; #pragma unroll
;             for (int ku = 0; ku < 2; ++ku)
; #pragma unroll
;               for (int r = 0; r < 16; ++r) S[ku][r] += bt[-(32 * ku + (r & 3) + 8 * (r >> 2) + 4 * hh)];
;           } else {
; #pragma unroll
;             for (int ku = 0; ku < 2; ++ku)
; #pragma unroll
;               for (int r = 0; r < 16; ++r) {
;                 int key = 32 * ku + (r & 3) + 8 * (r >> 2) + 4 * hh;
;                 int rel = qpos - (j * 64 + key);
;                 rel = min(256, max(-256, rel)) + 256;
;                 S[ku][r] += btab[rel];
;               }
;           }
;         }
;         float mx = -1e30f;
; #pragma unroll
;         for (int ku = 0; ku < 2; ++ku)
; #pragma unroll
;           for (int r = 0; r < 16; ++r) mx = fmaxf(mx, S[ku][r]);
;         if (__builtin_amdgcn_ballot_w64(first || mx > 6.f) != 0ull) {
;           mx = xhalf_max(mx);
;           const float d = first ? mx : (mx > 6.f ? mx : 0.f);
;           const float alpha = first ? 1.f : __builtin_amdgcn_exp2f(-d);
;           m_run += d;
;           lsum *= alpha;
; #pragma unroll
;           for (int ku = 0; ku < 2; ++ku)
; #pragma unroll
;             for (int r = 0; r < 16; ++r) S[ku][r] -= d;
; #pragma unroll
;           for (int du = 0; du < 2; ++du)
; #pragma unroll
;             for (int r = 0; r < 16; ++r) O[du][r] *= alpha;
;         }
.Lmy_w1_dn:
	v_mfma_f32_32x32x16_bf16 v[66:81], v[8:11], v[82:85], v[66:81]
	s_waitcnt lgkmcnt(9)
	v_mfma_f32_32x32x16_bf16 v[50:65], v[162:165], v[82:85], v[50:65]
	ds_read2_b64 v[162:165], v4 offset0:128 offset1:130
	v_mfma_f32_32x32x16_bf16 v[66:81], v[12:15], v[94:97], v[66:81]
	s_waitcnt lgkmcnt(9)
	v_mfma_f32_32x32x16_bf16 v[50:65], v[204:207], v[94:97], v[50:65]
	v_mfma_f32_32x32x16_bf16 v[66:81], v[146:149], v[90:93], v[66:81]
	s_waitcnt lgkmcnt(8)
	v_mfma_f32_32x32x16_bf16 v[50:65], v[208:211], v[90:93], v[50:65]
	v_mfma_f32_32x32x16_bf16 v[66:81], v[150:153], v[102:105], v[66:81]
	s_waitcnt lgkmcnt(7)
	v_mfma_f32_32x32x16_bf16 v[50:65], v[212:215], v[102:105], v[50:65]
	v_mfma_f32_32x32x16_bf16 v[66:81], v[154:157], v[98:101], v[66:81]
	ds_read2_b64 v[154:157], v4 offset0:132 offset1:134
	ds_read2_b64 v[146:149], v4 offset0:136 offset1:138
	ds_read2_b64 v[8:11], v4 offset0:140 offset1:142
	v_add_u32_e32 v4, 0x4000, v187
	ds_read2_b64 v[158:161], v4 offset0:224 offset1:226
	ds_read2_b64 v[150:153], v4 offset0:228 offset1:230
	ds_read2_b64 v[12:15], v4 offset0:232 offset1:234
	ds_read2_b64 v[4:7], v4 offset0:236 offset1:238
	s_waitcnt lgkmcnt(13)
	v_mfma_f32_32x32x16_bf16 v[50:65], v[216:219], v[98:101], v[50:65]
	s_setprio 0
	s_nop 1
	v_max3_f32 v16, v66, s38, v67
	v_max3_f32 v16, v16, v68, v69
	v_max3_f32 v16, v16, v70, v71
	v_max3_f32 v16, v16, v72, v73
	v_max3_f32 v16, v16, v74, v75
	v_max3_f32 v16, v16, v76, v77
	v_max3_f32 v16, v16, v78, v79
	v_max3_f32 v16, v16, v80, v81
	s_nop 1
	v_max3_f32 v16, v16, v50, v51
	v_max3_f32 v16, v16, v52, v53
	v_max3_f32 v16, v16, v54, v55
	v_max3_f32 v16, v16, v56, v57
	v_max3_f32 v16, v16, v58, v59
	v_max3_f32 v16, v16, v60, v61
	v_max3_f32 v16, v16, v62, v63
	v_max3_f32 v16, v16, v64, v65
	v_cmp_lt_f32_e32 vcc, s39, v16
	s_or_b64 vcc, s[0:1], vcc
	s_cbranch_vccz .LBB0_995
	v_mov_b32_e32 v17, v16
	s_nop 1
	v_permlane32_swap_b32_e32 v16, v17
	v_max_f32_e32 v17, v17, v17
	v_max_f32_e32 v16, v16, v16
	v_max_f32_e32 v16, v16, v17
	v_cmp_lt_f32_e32 vcc, s39, v16
	s_or_b64 vcc, s[0:1], vcc
	s_nop 0
	v_cndmask_b32_e32 v16, 0, v16, vcc
	v_exp_f32_e64 v17, -v16
	v_add_f32_e32 v2, v2, v16
	v_sub_f32_e32 v228, 0, v2
	v_mov_b32_e32 v229, v228
	v_mov_b32_e32 v230, v228
	v_mov_b32_e32 v231, v228
	v_mov_b32_e32 v232, v228
	v_mov_b32_e32 v233, v228
	v_mov_b32_e32 v234, v228
	v_mov_b32_e32 v235, v228
	v_mov_b32_e32 v236, v228
	v_mov_b32_e32 v237, v228
	v_mov_b32_e32 v238, v228
	v_mov_b32_e32 v239, v228
	v_mov_b32_e32 v240, v228
	v_mov_b32_e32 v241, v228
	v_mov_b32_e32 v242, v228
	v_mov_b32_e32 v243, v228
	v_cndmask_b32_e64 v204, v17, 1.0, s[0:1]
	v_mul_f32_e32 v177, v177, v204
	v_pk_add_f32 v[66:67], v[66:67], v[16:17] op_sel_hi:[1,0] neg_lo:[0,1] neg_hi:[0,1]
	v_pk_add_f32 v[68:69], v[68:69], v[16:17] op_sel_hi:[1,0] neg_lo:[0,1] neg_hi:[0,1]
	v_pk_add_f32 v[70:71], v[70:71], v[16:17] op_sel_hi:[1,0] neg_lo:[0,1] neg_hi:[0,1]
	v_pk_add_f32 v[72:73], v[72:73], v[16:17] op_sel_hi:[1,0] neg_lo:[0,1] neg_hi:[0,1]
	v_pk_add_f32 v[74:75], v[74:75], v[16:17] op_sel_hi:[1,0] neg_lo:[0,1] neg_hi:[0,1]
	v_pk_add_f32 v[76:77], v[76:77], v[16:17] op_sel_hi:[1,0] neg_lo:[0,1] neg_hi:[0,1]
	v_pk_add_f32 v[78:79], v[78:79], v[16:17] op_sel_hi:[1,0] neg_lo:[0,1] neg_hi:[0,1]
	v_pk_add_f32 v[80:81], v[80:81], v[16:17] op_sel_hi:[1,0] neg_lo:[0,1] neg_hi:[0,1]
	v_pk_add_f32 v[50:51], v[50:51], v[16:17] op_sel_hi:[1,0] neg_lo:[0,1] neg_hi:[0,1]
	v_pk_add_f32 v[52:53], v[52:53], v[16:17] op_sel_hi:[1,0] neg_lo:[0,1] neg_hi:[0,1]
	v_pk_add_f32 v[54:55], v[54:55], v[16:17] op_sel_hi:[1,0] neg_lo:[0,1] neg_hi:[0,1]
	v_pk_add_f32 v[56:57], v[56:57], v[16:17] op_sel_hi:[1,0] neg_lo:[0,1] neg_hi:[0,1]
	v_pk_add_f32 v[58:59], v[58:59], v[16:17] op_sel_hi:[1,0] neg_lo:[0,1] neg_hi:[0,1]
	v_pk_add_f32 v[60:61], v[60:61], v[16:17] op_sel_hi:[1,0] neg_lo:[0,1] neg_hi:[0,1]
	v_pk_add_f32 v[62:63], v[62:63], v[16:17] op_sel_hi:[1,0] neg_lo:[0,1] neg_hi:[0,1]
	v_pk_add_f32 v[64:65], v[64:65], v[16:17] op_sel_hi:[1,0] neg_lo:[0,1] neg_hi:[0,1]
	v_pk_mul_f32 v[48:49], v[48:49], v[204:205] op_sel_hi:[1,0]
	v_pk_mul_f32 v[46:47], v[46:47], v[204:205] op_sel_hi:[1,0]
	v_pk_mul_f32 v[44:45], v[44:45], v[204:205] op_sel_hi:[1,0]
	v_pk_mul_f32 v[42:43], v[42:43], v[204:205] op_sel_hi:[1,0]
	v_pk_mul_f32 v[40:41], v[40:41], v[204:205] op_sel_hi:[1,0]
	v_pk_mul_f32 v[38:39], v[38:39], v[204:205] op_sel_hi:[1,0]
	v_pk_mul_f32 v[36:37], v[36:37], v[204:205] op_sel_hi:[1,0]
	v_pk_mul_f32 v[34:35], v[34:35], v[204:205] op_sel_hi:[1,0]
	v_pk_mul_f32 v[32:33], v[32:33], v[204:205] op_sel_hi:[1,0]
	v_pk_mul_f32 v[30:31], v[30:31], v[204:205] op_sel_hi:[1,0]
	v_pk_mul_f32 v[28:29], v[28:29], v[204:205] op_sel_hi:[1,0]
	v_pk_mul_f32 v[26:27], v[26:27], v[204:205] op_sel_hi:[1,0]
	v_pk_mul_f32 v[24:25], v[24:25], v[204:205] op_sel_hi:[1,0]
	v_pk_mul_f32 v[22:23], v[22:23], v[204:205] op_sel_hi:[1,0]
	v_pk_mul_f32 v[20:21], v[20:21], v[204:205] op_sel_hi:[1,0]
	v_pk_mul_f32 v[18:19], v[18:19], v[204:205] op_sel_hi:[1,0]

; template <int DQK, int MODE> ...
;     ...
;   auto step = [&](TRegs& R, int it) -> bool {
;     const int j = jstart + dir * it;
;     const int st = it & 1;
;     lstore(R, st);
;     if (MODE == 2) {
;       int alive = (carry != 0.f) ? 1 : 0;
;       if (!__syncthreads_or(alive)) return false;
;     } else {
;       __syncthreads();
;     }
;     if (it + 2 < ntile) gload(R, j + 2 * dir);
;     __builtin_amdgcn_sched_barrier(0);
;     if (active && j <= hiw && j >= low) {
;       const u16* Ks = lds + st * STG;
;       const u16* Vs = Ks + KT;
;       f32x16 S[2];
;       const bool far = (MODE == 1) && ((qpos0 + 32 * w) - (j * 64 + 63) >= 256);
;       const float cinit = (MODE != 2) ? (-m_run + (far ? btab[512] : 0.f)) : 0.f;
;       {
;         bf16x8 kf[2][NKK];
; #pragma unroll
;         for (int ku = 0; ku < 2; ++ku)
; #pragma unroll
;           for (int kk = 0; kk < NKK; ++kk)
;             kf[ku][kk] = *(const bf16x8*)(Ks + (ku * 32 + ql) * KST + kk * 16 + hh * 8);
;         __builtin_amdgcn_sched_barrier(0);
; #pragma unroll
;         for (int ku = 0; ku < 2; ++ku)
; #pragma unroll
;           for (int r = 0; r < 16; ++r) S[ku][r] = cinit;
; #pragma unroll
;         for (int kk = 0; kk < NKK; ++kk)
; #pragma unroll
;           for (int ku = 0; ku < 2; ++ku)
;             S[ku] = __builtin_amdgcn_mfma_f32_32x32x16_bf16(kf[ku][kk], qf[kk], S[ku], 0, 0, 0);
;       }
.Lmy_w3_dn:
.LBB0_996:
	s_or_b64 exec, exec, s[16:17]
	s_add_i32 s7, s3, -3
	s_cmp_ge_i32 s7, s2
	s_cbranch_scc1 .LBB0_989
	v_add_u32_e32 v220, s4, v171
	v_add_u32_e32 v220, 0xfc0000c0, v220
	v_add_u32_e32 v222, s4, v173
	v_mad_i64_i32 v[220:221], s[16:17], v220, s85, v[178:179]
	v_add_u32_e32 v222, 0xfc0000c0, v222
	v_mad_i64_i32 v[222:223], s[16:17], v222, s85, v[180:181]
	v_add_u32_e32 v224, s4, v175
	v_add_u32_e32 v224, 0xfc0000c0, v224
	v_mad_i64_i32 v[224:225], s[16:17], v224, s85, v[182:183]
	v_lshl_add_u64 v[244:245], v[188:189], 0, s[10:11]
	v_add_co_u32_e32 v244, vcc, 0x6000, v244
	s_nop 1
	v_addc_co_u32_e32 v245, vcc, -2, v245, vcc
	v_lshl_add_u64 v[248:249], v[190:191], 0, s[10:11]
	v_add_co_u32_e32 v248, vcc, 0x6000, v248
	s_nop 1
	v_addc_co_u32_e32 v249, vcc, -2, v249, vcc
	s_add_i32 s13, s6, 0xffeffffe
	v_cmp_le_i32_e32 vcc, s13, v199
	s_and_b64 s[6:7], s[14:15], vcc
	v_cmp_ge_u32_e32 vcc, s13, v200
	s_and_b64 s[6:7], s[6:7], vcc
	s_cmp_gt_i32 s3, s2
	s_waitcnt lgkmcnt(0)
	s_barrier
	s_cbranch_scc1 .LBB0_999
	global_load_dwordx4 v[122:125], v[220:221], off
	global_load_dwordx4 v[126:129], v[222:223], off
	global_load_dwordx4 v[134:137], v[224:225], off
	global_load_dwordx4 v[138:141], v[244:245], off
	global_load_dwordx4 v[142:145], v[248:249], off
.LBB0_999:
	s_and_saveexec_b64 s[16:17], s[6:7]
	s_cbranch_execz .Lmy_ia1_a
	ds_read_b128 v[4:7], v185 offset:23040
	ds_read_b128 v[8:11], v185 offset:23072
	ds_read_b128 v[12:15], v185 offset:23104
	ds_read_b128 v[146:149], v185 offset:23136
	ds_read_b128 v[150:153], v185 offset:23168
	ds_read_b128 v[154:157], v185 offset:23200
	ds_read_b128 v[158:161], v185 offset:29696
	ds_read_b128 v[162:165], v185 offset:29728
	ds_read_b128 v[204:207], v185 offset:29760
	ds_read_b128 v[208:211], v185 offset:29792
	ds_read_b128 v[212:215], v185 offset:29824
	ds_read_b128 v[216:219], v185 offset:29856
	s_setprio 1
	s_waitcnt lgkmcnt(11)
	v_mfma_f32_32x32x16_bf16 v[66:81], v[4:7], v[86:89], v[228:243]
	v_add_u32_e32 v4, 0x8800, v187
	s_waitcnt lgkmcnt(5)
	v_mfma_f32_32x32x16_bf16 v[50:65], v[158:161], v[86:89], v[228:243]
	s_cmp_gt_i32 s3, s2
	s_cbranch_scc1 .Lmy_w2_nl
	v_add_u32_e32 v226, 0x3400, v184
	s_waitcnt vmcnt(9)
	ds_write_b128 v201, v[106:109]
	s_waitcnt vmcnt(8)
	ds_write_b128 v202, v[110:113]
	s_waitcnt vmcnt(7)
	ds_write_b128 v203, v[114:117]
	s_waitcnt vmcnt(6)
	ds_write2_b64 v226, v[118:119], v[120:121] offset1:1
	v_add_u32_e32 v226, 0x3400, v186
	s_waitcnt vmcnt(5)
	ds_write2_b64 v226, v[130:131], v[132:133] offset1:1
	s_branch .Lmy_w2_dn

; template <int DQK, int MODE> ...
;     ...
;         for (int kk = 0; kk < NKK; ++kk)
; #pragma unroll
;           for (int ku = 0; ku < 2; ++ku)
;             S[ku] = __builtin_amdgcn_mfma_f32_32x32x16_bf16(kf[ku][kk], qf[kk], S[ku], 0, 0, 0);
;       }
;       u32x4 vf[2][4];
;       if (MODE != 2) {
; #pragma unroll
;         for (int du = 0; du < 2; ++du)
; #pragma unroll
;           for (int s4 = 0; s4 < 4; ++s4) {
;             const u16* vp = Vs + (du * 32 + ql) * VST + 16 * s4 + 4 * hh;
;             u32x2 a = *(const u32x2*)vp;
;             u32x2 b = *(const u32x2*)(vp + 8);
;             vf[du][s4] = (u32x4){a.x, a.y, b.x, b.y};
;           }
;         __builtin_amdgcn_sched_barrier(0);
;       }
;       bf16x8 pf[4];
;       if (MODE != 2) {
;         if (MODE == 1 && !far) {
;           const bool noclip = ((qpos0 + 32 * w + 31) - j * 64 <= 256) && ((qpos0 + 32 * w) - (j * 64 + 63) >= -256);
;           if (noclip) {
;             const float* bt = btab + 256 + qpos - j * 64;
; #pragma unroll
;             for (int ku = 0; ku < 2; ++ku)
; #pragma unroll
;               for (int r = 0; r < 16; ++r) S[ku][r] += bt[-(32 * ku + (r & 3) + 8 * (r >> 2) + 4 * hh)];
;           } else {
; #pragma unroll
;             for (int ku = 0; ku < 2; ++ku)
; #pragma unroll
;               for (int r = 0; r < 16; ++r) {
;                 int key = 32 * ku + (r & 3) + 8 * (r >> 2) + 4 * hh;
;                 int rel = qpos - (j * 64 + key);
;                 rel = min(256, max(-256, rel)) + 256;
;                 S[ku][r] += btab[rel];
;               }
;           }
;         }
;         float mx = -1e30f;
; #pragma unroll
;         for (int ku = 0; ku < 2; ++ku)
; #pragma unroll
;           for (int r = 0; r < 16; ++r) mx = fmaxf(mx, S[ku][r]);
;         if (__builtin_amdgcn_ballot_w64(first || mx > 6.f) != 0ull) {
;           mx = xhalf_max(mx);
;           const float d = first ? mx : (mx > 6.f ? mx : 0.f);
;           const float alpha = first ? 1.f : __builtin_amdgcn_exp2f(-d);
;           m_run += d;
;           lsum *= alpha;
; #pragma unroll
;           for (int ku = 0; ku < 2; ++ku)
; #pragma unroll
;             for (int r = 0; r < 16; ++r) S[ku][r] -= d;
; #pragma unroll
;           for (int du = 0; du < 2; ++du)
; #pragma unroll
;             for (int r = 0; r < 16; ++r) O[du][r] *= alpha;
;         }
.Lmy_w2_dn:
	v_mfma_f32_32x32x16_bf16 v[66:81], v[8:11], v[82:85], v[66:81]
	s_waitcnt lgkmcnt(9)
	v_mfma_f32_32x32x16_bf16 v[50:65], v[162:165], v[82:85], v[50:65]
	ds_read2_b64 v[162:165], v4 offset0:192 offset1:194
	v_mfma_f32_32x32x16_bf16 v[66:81], v[12:15], v[94:97], v[66:81]
	s_waitcnt lgkmcnt(9)
	v_mfma_f32_32x32x16_bf16 v[50:65], v[204:207], v[94:97], v[50:65]
	v_mfma_f32_32x32x16_bf16 v[66:81], v[146:149], v[90:93], v[66:81]
	s_waitcnt lgkmcnt(8)
	v_mfma_f32_32x32x16_bf16 v[50:65], v[208:211], v[90:93], v[50:65]
	v_mfma_f32_32x32x16_bf16 v[66:81], v[150:153], v[102:105], v[66:81]
	s_waitcnt lgkmcnt(7)
	v_mfma_f32_32x32x16_bf16 v[50:65], v[212:215], v[102:105], v[50:65]
	v_mfma_f32_32x32x16_bf16 v[66:81], v[154:157], v[98:101], v[66:81]
	ds_read2_b64 v[154:157], v4 offset0:196 offset1:198
	ds_read2_b64 v[146:149], v4 offset0:200 offset1:202
	ds_read2_b64 v[8:11], v4 offset0:204 offset1:206
	v_add_u32_e32 v4, 0xa000, v187
	ds_read2_b64 v[158:161], v4 offset0:32 offset1:34
	ds_read2_b64 v[150:153], v4 offset0:36 offset1:38
	ds_read2_b64 v[12:15], v4 offset0:40 offset1:42
	ds_read2_b64 v[4:7], v4 offset0:44 offset1:46
	s_waitcnt lgkmcnt(13)
	v_mfma_f32_32x32x16_bf16 v[50:65], v[216:219], v[98:101], v[50:65]
	s_setprio 0
	s_nop 1
	v_max3_f32 v16, v66, s38, v67
	v_max3_f32 v16, v16, v68, v69
	v_max3_f32 v16, v16, v70, v71
	v_max3_f32 v16, v16, v72, v73
	v_max3_f32 v16, v16, v74, v75
	v_max3_f32 v16, v16, v76, v77
	v_max3_f32 v16, v16, v78, v79
	v_max3_f32 v16, v16, v80, v81
	s_nop 1
	v_max3_f32 v16, v16, v50, v51
	v_max3_f32 v16, v16, v52, v53
	v_max3_f32 v16, v16, v54, v55
	v_max3_f32 v16, v16, v56, v57
	v_max3_f32 v16, v16, v58, v59
	v_max3_f32 v16, v16, v60, v61
	v_max3_f32 v16, v16, v62, v63
	v_max3_f32 v16, v16, v64, v65
	v_cmp_lt_f32_e32 vcc, s39, v16
	s_or_b64 vcc, s[0:1], vcc
	s_cbranch_vccz .LBB0_987
	v_mov_b32_e32 v17, v16
	s_nop 1
	v_permlane32_swap_b32_e32 v16, v17
	v_max_f32_e32 v17, v17, v17
	v_max_f32_e32 v16, v16, v16
	v_max_f32_e32 v16, v16, v17
	v_cmp_lt_f32_e32 vcc, s39, v16
	s_or_b64 vcc, s[0:1], vcc
	s_nop 0
	v_cndmask_b32_e32 v16, 0, v16, vcc
	v_exp_f32_e64 v17, -v16
	v_add_f32_e32 v2, v2, v16
	v_sub_f32_e32 v228, 0, v2
	v_mov_b32_e32 v229, v228
	v_mov_b32_e32 v230, v228
	v_mov_b32_e32 v231, v228
	v_mov_b32_e32 v232, v228
	v_mov_b32_e32 v233, v228
	v_mov_b32_e32 v234, v228
	v_mov_b32_e32 v235, v228
	v_mov_b32_e32 v236, v228
	v_mov_b32_e32 v237, v228
	v_mov_b32_e32 v238, v228
	v_mov_b32_e32 v239, v228
	v_mov_b32_e32 v240, v228
	v_mov_b32_e32 v241, v228
	v_mov_b32_e32 v242, v228
	v_mov_b32_e32 v243, v228
	v_cndmask_b32_e64 v204, v17, 1.0, s[0:1]
	v_mul_f32_e32 v177, v177, v204
	v_pk_add_f32 v[66:67], v[66:67], v[16:17] op_sel_hi:[1,0] neg_lo:[0,1] neg_hi:[0,1]
	v_pk_add_f32 v[68:69], v[68:69], v[16:17] op_sel_hi:[1,0] neg_lo:[0,1] neg_hi:[0,1]
	v_pk_add_f32 v[70:71], v[70:71], v[16:17] op_sel_hi:[1,0] neg_lo:[0,1] neg_hi:[0,1]
	v_pk_add_f32 v[72:73], v[72:73], v[16:17] op_sel_hi:[1,0] neg_lo:[0,1] neg_hi:[0,1]
	v_pk_add_f32 v[74:75], v[74:75], v[16:17] op_sel_hi:[1,0] neg_lo:[0,1] neg_hi:[0,1]
	v_pk_add_f32 v[76:77], v[76:77], v[16:17] op_sel_hi:[1,0] neg_lo:[0,1] neg_hi:[0,1]
	v_pk_add_f32 v[78:79], v[78:79], v[16:17] op_sel_hi:[1,0] neg_lo:[0,1] neg_hi:[0,1]
	v_pk_add_f32 v[80:81], v[80:81], v[16:17] op_sel_hi:[1,0] neg_lo:[0,1] neg_hi:[0,1]
	v_pk_add_f32 v[50:51], v[50:51], v[16:17] op_sel_hi:[1,0] neg_lo:[0,1] neg_hi:[0,1]
	v_pk_add_f32 v[52:53], v[52:53], v[16:17] op_sel_hi:[1,0] neg_lo:[0,1] neg_hi:[0,1]
	v_pk_add_f32 v[54:55], v[54:55], v[16:17] op_sel_hi:[1,0] neg_lo:[0,1] neg_hi:[0,1]
	v_pk_add_f32 v[56:57], v[56:57], v[16:17] op_sel_hi:[1,0] neg_lo:[0,1] neg_hi:[0,1]
	v_pk_add_f32 v[58:59], v[58:59], v[16:17] op_sel_hi:[1,0] neg_lo:[0,1] neg_hi:[0,1]
	v_pk_add_f32 v[60:61], v[60:61], v[16:17] op_sel_hi:[1,0] neg_lo:[0,1] neg_hi:[0,1]
	v_pk_add_f32 v[62:63], v[62:63], v[16:17] op_sel_hi:[1,0] neg_lo:[0,1] neg_hi:[0,1]
	v_pk_add_f32 v[64:65], v[64:65], v[16:17] op_sel_hi:[1,0] neg_lo:[0,1] neg_hi:[0,1]
	v_pk_mul_f32 v[48:49], v[48:49], v[204:205] op_sel_hi:[1,0]
	v_pk_mul_f32 v[46:47], v[46:47], v[204:205] op_sel_hi:[1,0]
	v_pk_mul_f32 v[44:45], v[44:45], v[204:205] op_sel_hi:[1,0]
	v_pk_mul_f32 v[42:43], v[42:43], v[204:205] op_sel_hi:[1,0]
	v_pk_mul_f32 v[40:41], v[40:41], v[204:205] op_sel_hi:[1,0]
	v_pk_mul_f32 v[38:39], v[38:39], v[204:205] op_sel_hi:[1,0]
	v_pk_mul_f32 v[36:37], v[36:37], v[204:205] op_sel_hi:[1,0]
	v_pk_mul_f32 v[34:35], v[34:35], v[204:205] op_sel_hi:[1,0]
	v_pk_mul_f32 v[32:33], v[32:33], v[204:205] op_sel_hi:[1,0]
	v_pk_mul_f32 v[30:31], v[30:31], v[204:205] op_sel_hi:[1,0]
	v_pk_mul_f32 v[28:29], v[28:29], v[204:205] op_sel_hi:[1,0]
	v_pk_mul_f32 v[26:27], v[26:27], v[204:205] op_sel_hi:[1,0]
	v_pk_mul_f32 v[24:25], v[24:25], v[204:205] op_sel_hi:[1,0]
	v_pk_mul_f32 v[22:23], v[22:23], v[204:205] op_sel_hi:[1,0]
	v_pk_mul_f32 v[20:21], v[20:21], v[204:205] op_sel_hi:[1,0]
	v_pk_mul_f32 v[18:19], v[18:19], v[204:205] op_sel_hi:[1,0]
	s_branch .LBB0_987

; template <int DQK, int MODE> ...
;     ...
;   auto step = [&](TRegs& R, int it) -> bool {
;     const int j = jstart + dir * it;
;     const int st = it & 1;
;     lstore(R, st);
;     if (MODE == 2) {
;       int alive = (carry != 0.f) ? 1 : 0;
;       if (!__syncthreads_or(alive)) return false;
;     } else {
;       __syncthreads();
;     }
;     if (it + 2 < ntile) gload(R, j + 2 * dir);
;     __builtin_amdgcn_sched_barrier(0);
;     if (active && j <= hiw && j >= low) {
;       const u16* Ks = lds + st * STG;
;       const u16* Vs = Ks + KT;
;       f32x16 S[2];
;       const bool far = (MODE == 1) && ((qpos0 + 32 * w) - (j * 64 + 63) >= 256);
;       const float cinit = (MODE != 2) ? (-m_run + (far ? btab[512] : 0.f)) : 0.f;
;       {
;         bf16x8 kf[2][NKK];
; #pragma unroll
;         for (int ku = 0; ku < 2; ++ku)
; #pragma unroll
;           for (int kk = 0; kk < NKK; ++kk)
;             kf[ku][kk] = *(const bf16x8*)(Ks + (ku * 32 + ql) * KST + kk * 16 + hh * 8);
;         __builtin_amdgcn_sched_barrier(0);
; #pragma unroll
;         for (int ku = 0; ku < 2; ++ku)
; #pragma unroll
;           for (int r = 0; r < 16; ++r) S[ku][r] = cinit;
; #pragma unroll
;         for (int kk = 0; kk < NKK; ++kk)
; #pragma unroll
;           for (int ku = 0; ku < 2; ++ku)
;             S[ku] = __builtin_amdgcn_mfma_f32_32x32x16_bf16(kf[ku][kk], qf[kk], S[ku], 0, 0, 0);
;       }
.LBB0_2127:
	v_add_u32_e32 v220, s9, v169
	v_add_u32_e32 v220, 0xfc000080, v220
	v_add_u32_e32 v222, s9, v171
	v_mad_i64_i32 v[220:221], s[14:15], v220, s87, v[176:177]
	v_add_u32_e32 v222, 0xfc000080, v222
	v_mad_i64_i32 v[222:223], s[14:15], v222, s87, v[178:179]
	v_add_u32_e32 v224, s9, v173
	v_add_u32_e32 v224, 0xfc000080, v224
	v_mad_i64_i32 v[224:225], s[14:15], v224, s87, v[180:181]
	v_lshl_add_u64 v[244:245], v[186:187], 0, s[2:3]
	v_add_co_u32_e32 v244, vcc, 0x4000, v244
	s_nop 1
	v_addc_co_u32_e32 v245, vcc, -2, v245, vcc
	v_lshl_add_u64 v[248:249], v[188:189], 0, s[2:3]
	v_add_co_u32_e32 v248, vcc, 0x4000, v248
	s_nop 1
	v_addc_co_u32_e32 v249, vcc, -2, v249, vcc
	s_add_i32 s21, s8, s17
	s_add_i32 s30, s21, 0xffeffffd
	v_cmp_le_i32_e32 vcc, s30, v197
	s_and_b64 s[14:15], s[12:13], vcc
	v_cmp_ge_u32_e32 vcc, s30, v199
	s_and_b64 s[30:31], s[14:15], vcc
	s_add_i32 s18, s17, -1
	s_cmp_gt_i32 s18, s16
	s_waitcnt lgkmcnt(0)
	s_barrier
	s_cbranch_scc1 .LBB0_2129
	global_load_dwordx4 v[104:107], v[220:221], off
	global_load_dwordx4 v[108:111], v[222:223], off
	global_load_dwordx4 v[112:115], v[224:225], off
	global_load_dwordx4 v[116:119], v[244:245], off
	global_load_dwordx4 v[128:131], v[248:249], off
.LBB0_2129:
	s_and_saveexec_b64 s[14:15], s[30:31]
	s_cbranch_execz .Lmy_ia0_b
	ds_read_b128 v[2:5], v183
	ds_read_b128 v[6:9], v183 offset:32
	ds_read_b128 v[10:13], v183 offset:64
	ds_read_b128 v[144:147], v183 offset:96
	ds_read_b128 v[148:151], v183 offset:128
	ds_read_b128 v[152:155], v183 offset:160
	ds_read_b128 v[156:159], v183 offset:6656
	ds_read_b128 v[160:163], v183 offset:6688
	ds_read_b128 v[204:207], v183 offset:6720
	ds_read_b128 v[208:211], v183 offset:6752
	ds_read_b128 v[212:215], v183 offset:6784
	ds_read_b128 v[216:219], v183 offset:6816
	s_setprio 1
	s_waitcnt lgkmcnt(11)
	v_mfma_f32_32x32x16_bf16 v[64:79], v[2:5], v[84:87], v[228:243]
	v_add_u32_e32 v2, 0x3000, v185
	s_waitcnt lgkmcnt(5)
	v_mfma_f32_32x32x16_bf16 v[48:63], v[156:159], v[84:87], v[228:243]
	s_cmp_gt_i32 s18, s16
	s_cbranch_scc1 .Lmy_w5_nl
	v_add_u32_e32 v226, 0x8e00, v182
	s_waitcnt vmcnt(9)
	ds_write_b128 v200, v[120:123] offset:23040
	s_waitcnt vmcnt(8)
	ds_write_b128 v201, v[124:127] offset:23040
	s_waitcnt vmcnt(7)
	ds_write_b128 v202, v[132:135] offset:23040
	s_waitcnt vmcnt(6)
	ds_write2_b64 v226, v[136:137], v[138:139] offset1:1
	v_add_u32_e32 v226, 0x8e00, v184
	s_waitcnt vmcnt(5)
	ds_write2_b64 v226, v[140:141], v[142:143] offset1:1
	s_branch .Lmy_w5_dn

; template <int DQK, int MODE> ...
;     ...
;         for (int kk = 0; kk < NKK; ++kk)
; #pragma unroll
;           for (int ku = 0; ku < 2; ++ku)
;             S[ku] = __builtin_amdgcn_mfma_f32_32x32x16_bf16(kf[ku][kk], qf[kk], S[ku], 0, 0, 0);
;       }
;       u32x4 vf[2][4];
;       if (MODE != 2) {
; #pragma unroll
;         for (int du = 0; du < 2; ++du)
; #pragma unroll
;           for (int s4 = 0; s4 < 4; ++s4) {
;             const u16* vp = Vs + (du * 32 + ql) * VST + 16 * s4 + 4 * hh;
;             u32x2 a = *(const u32x2*)vp;
;             u32x2 b = *(const u32x2*)(vp + 8);
;             vf[du][s4] = (u32x4){a.x, a.y, b.x, b.y};
;           }
;         __builtin_amdgcn_sched_barrier(0);
;       }
;       bf16x8 pf[4];
;       if (MODE != 2) {
;         if (MODE == 1 && !far) {
;           const bool noclip = ((qpos0 + 32 * w + 31) - j * 64 <= 256) && ((qpos0 + 32 * w) - (j * 64 + 63) >= -256);
;           if (noclip) {
;             const float* bt = btab + 256 + qpos - j * 64;
; #pragma unroll
;             for (int ku = 0; ku < 2; ++ku)
; #pragma unroll
;               for (int r = 0; r < 16; ++r) S[ku][r] += bt[-(32 * ku + (r & 3) + 8 * (r >> 2) + 4 * hh)];
;           } else {
; #pragma unroll
;             for (int ku = 0; ku < 2; ++ku)
; #pragma unroll
;               for (int r = 0; r < 16; ++r) {
;                 int key = 32 * ku + (r & 3) + 8 * (r >> 2) + 4 * hh;
;                 int rel = qpos - (j * 64 + key);
;                 rel = min(256, max(-256, rel)) + 256;
;                 S[ku][r] += btab[rel];
;               }
;           }
;         }
;         float mx = -1e30f;
; #pragma unroll
;         for (int ku = 0; ku < 2; ++ku)
; #pragma unroll
;           for (int r = 0; r < 16; ++r) mx = fmaxf(mx, S[ku][r]);
;         if (__builtin_amdgcn_ballot_w64(first || mx > 6.f) != 0ull) {
;           mx = xhalf_max(mx);
;           const float d = first ? mx : (mx > 6.f ? mx : 0.f);
;           const float alpha = first ? 1.f : __builtin_amdgcn_exp2f(-d);
;           m_run += d;
;           lsum *= alpha;
; #pragma unroll
;           for (int ku = 0; ku < 2; ++ku)
; #pragma unroll
;             for (int r = 0; r < 16; ++r) S[ku][r] -= d;
; #pragma unroll
;           for (int du = 0; du < 2; ++du)
; #pragma unroll
;             for (int r = 0; r < 16; ++r) O[du][r] *= alpha;
;         }
.Lmy_w5_dn:
	v_mfma_f32_32x32x16_bf16 v[64:79], v[6:9], v[80:83], v[64:79]
	s_waitcnt lgkmcnt(9)
	v_mfma_f32_32x32x16_bf16 v[48:63], v[160:163], v[80:83], v[48:63]
	ds_read2_b64 v[160:163], v2 offset0:128 offset1:130
	v_mfma_f32_32x32x16_bf16 v[64:79], v[10:13], v[92:95], v[64:79]
	s_waitcnt lgkmcnt(9)
	v_mfma_f32_32x32x16_bf16 v[48:63], v[204:207], v[92:95], v[48:63]
	v_mfma_f32_32x32x16_bf16 v[64:79], v[144:147], v[88:91], v[64:79]
	s_waitcnt lgkmcnt(8)
	v_mfma_f32_32x32x16_bf16 v[48:63], v[208:211], v[88:91], v[48:63]
	v_mfma_f32_32x32x16_bf16 v[64:79], v[148:151], v[100:103], v[64:79]
	s_waitcnt lgkmcnt(7)
	v_mfma_f32_32x32x16_bf16 v[48:63], v[212:215], v[100:103], v[48:63]
	v_mfma_f32_32x32x16_bf16 v[64:79], v[152:155], v[96:99], v[64:79]
	ds_read2_b64 v[152:155], v2 offset0:132 offset1:134
	ds_read2_b64 v[144:147], v2 offset0:136 offset1:138
	ds_read2_b64 v[6:9], v2 offset0:140 offset1:142
	v_add_u32_e32 v2, 0x4000, v185
	ds_read2_b64 v[156:159], v2 offset0:224 offset1:226
	ds_read2_b64 v[148:151], v2 offset0:228 offset1:230
	ds_read2_b64 v[10:13], v2 offset0:232 offset1:234
	ds_read2_b64 v[2:5], v2 offset0:236 offset1:238
	s_waitcnt lgkmcnt(13)
	v_mfma_f32_32x32x16_bf16 v[48:63], v[216:219], v[96:99], v[48:63]
	s_setprio 0
	s_nop 1
	v_max3_f32 v14, v64, s96, v65
	v_max3_f32 v14, v14, v66, v67
	v_max3_f32 v14, v14, v68, v69
	v_max3_f32 v14, v14, v70, v71
	v_max3_f32 v14, v14, v72, v73
	v_max3_f32 v14, v14, v74, v75
	v_max3_f32 v14, v14, v76, v77
	v_max3_f32 v14, v14, v78, v79
	s_nop 1
	v_max3_f32 v14, v14, v48, v49
	v_max3_f32 v14, v14, v50, v51
	v_max3_f32 v14, v14, v52, v53
	v_max3_f32 v14, v14, v54, v55
	v_max3_f32 v14, v14, v56, v57
	v_max3_f32 v14, v14, v58, v59
	v_max3_f32 v14, v14, v60, v61
	v_max3_f32 v14, v14, v62, v63
	v_cmp_lt_f32_e32 vcc, s97, v14
	s_or_b64 vcc, s[10:11], vcc
	s_cbranch_vccz .LBB0_2132
	v_mov_b32_e32 v15, v14
	s_nop 1
	v_permlane32_swap_b32_e32 v14, v15
	v_max_f32_e32 v15, v15, v15
	v_max_f32_e32 v14, v14, v14
	v_max_f32_e32 v14, v14, v15
	v_cmp_lt_f32_e32 vcc, s97, v14
	s_or_b64 vcc, s[10:11], vcc
	s_nop 0
	v_cndmask_b32_e32 v14, 0, v14, vcc
	v_exp_f32_e64 v15, -v14
	v_add_f32_e32 v0, v0, v14
	v_sub_f32_e32 v228, 0, v0
	v_mov_b32_e32 v229, v228
	v_mov_b32_e32 v230, v228
	v_mov_b32_e32 v231, v228
	v_mov_b32_e32 v232, v228
	v_mov_b32_e32 v233, v228
	v_mov_b32_e32 v234, v228
	v_mov_b32_e32 v235, v228
	v_mov_b32_e32 v236, v228
	v_mov_b32_e32 v237, v228
	v_mov_b32_e32 v238, v228
	v_mov_b32_e32 v239, v228
	v_mov_b32_e32 v240, v228
	v_mov_b32_e32 v241, v228
	v_mov_b32_e32 v242, v228
	v_mov_b32_e32 v243, v228
	v_cndmask_b32_e64 v204, v15, 1.0, s[10:11]
	v_mul_f32_e32 v175, v175, v204
	v_pk_add_f32 v[64:65], v[64:65], v[14:15] op_sel_hi:[1,0] neg_lo:[0,1] neg_hi:[0,1]
	v_pk_add_f32 v[66:67], v[66:67], v[14:15] op_sel_hi:[1,0] neg_lo:[0,1] neg_hi:[0,1]
	v_pk_add_f32 v[68:69], v[68:69], v[14:15] op_sel_hi:[1,0] neg_lo:[0,1] neg_hi:[0,1]
	v_pk_add_f32 v[70:71], v[70:71], v[14:15] op_sel_hi:[1,0] neg_lo:[0,1] neg_hi:[0,1]
	v_pk_add_f32 v[72:73], v[72:73], v[14:15] op_sel_hi:[1,0] neg_lo:[0,1] neg_hi:[0,1]
	v_pk_add_f32 v[74:75], v[74:75], v[14:15] op_sel_hi:[1,0] neg_lo:[0,1] neg_hi:[0,1]
	v_pk_add_f32 v[76:77], v[76:77], v[14:15] op_sel_hi:[1,0] neg_lo:[0,1] neg_hi:[0,1]
	v_pk_add_f32 v[78:79], v[78:79], v[14:15] op_sel_hi:[1,0] neg_lo:[0,1] neg_hi:[0,1]
	v_pk_add_f32 v[48:49], v[48:49], v[14:15] op_sel_hi:[1,0] neg_lo:[0,1] neg_hi:[0,1]
	v_pk_add_f32 v[50:51], v[50:51], v[14:15] op_sel_hi:[1,0] neg_lo:[0,1] neg_hi:[0,1]
	v_pk_add_f32 v[52:53], v[52:53], v[14:15] op_sel_hi:[1,0] neg_lo:[0,1] neg_hi:[0,1]
	v_pk_add_f32 v[54:55], v[54:55], v[14:15] op_sel_hi:[1,0] neg_lo:[0,1] neg_hi:[0,1]
	v_pk_add_f32 v[56:57], v[56:57], v[14:15] op_sel_hi:[1,0] neg_lo:[0,1] neg_hi:[0,1]
	v_pk_add_f32 v[58:59], v[58:59], v[14:15] op_sel_hi:[1,0] neg_lo:[0,1] neg_hi:[0,1]
	v_pk_add_f32 v[60:61], v[60:61], v[14:15] op_sel_hi:[1,0] neg_lo:[0,1] neg_hi:[0,1]
	v_pk_add_f32 v[62:63], v[62:63], v[14:15] op_sel_hi:[1,0] neg_lo:[0,1] neg_hi:[0,1]
	v_pk_mul_f32 v[46:47], v[46:47], v[204:205] op_sel_hi:[1,0]
	v_pk_mul_f32 v[44:45], v[44:45], v[204:205] op_sel_hi:[1,0]
	v_pk_mul_f32 v[42:43], v[42:43], v[204:205] op_sel_hi:[1,0]
	v_pk_mul_f32 v[40:41], v[40:41], v[204:205] op_sel_hi:[1,0]
	v_pk_mul_f32 v[38:39], v[38:39], v[204:205] op_sel_hi:[1,0]
	v_pk_mul_f32 v[36:37], v[36:37], v[204:205] op_sel_hi:[1,0]
	v_pk_mul_f32 v[34:35], v[34:35], v[204:205] op_sel_hi:[1,0]
	v_pk_mul_f32 v[32:33], v[32:33], v[204:205] op_sel_hi:[1,0]
	v_pk_mul_f32 v[30:31], v[30:31], v[204:205] op_sel_hi:[1,0]
	v_pk_mul_f32 v[28:29], v[28:29], v[204:205] op_sel_hi:[1,0]
	v_pk_mul_f32 v[26:27], v[26:27], v[204:205] op_sel_hi:[1,0]
	v_pk_mul_f32 v[24:25], v[24:25], v[204:205] op_sel_hi:[1,0]
	v_pk_mul_f32 v[22:23], v[22:23], v[204:205] op_sel_hi:[1,0]
	v_pk_mul_f32 v[20:21], v[20:21], v[204:205] op_sel_hi:[1,0]
	v_pk_mul_f32 v[18:19], v[18:19], v[204:205] op_sel_hi:[1,0]
	v_pk_mul_f32 v[16:17], v[16:17], v[204:205] op_sel_hi:[1,0]

; template <int DQK, int MODE> ...
;     ...
;   auto step = [&](TRegs& R, int it) -> bool {
;     const int j = jstart + dir * it;
;     const int st = it & 1;
;     lstore(R, st);
;     if (MODE == 2) {
;       int alive = (carry != 0.f) ? 1 : 0;
;       if (!__syncthreads_or(alive)) return false;
;     } else {
;       __syncthreads();
;     }
;     if (it + 2 < ntile) gload(R, j + 2 * dir);
;     __builtin_amdgcn_sched_barrier(0);
;     if (active && j <= hiw && j >= low) {
;       const u16* Ks = lds + st * STG;
;       const u16* Vs = Ks + KT;
;       f32x16 S[2];
;       const bool far = (MODE == 1) && ((qpos0 + 32 * w) - (j * 64 + 63) >= 256);
;       const float cinit = (MODE != 2) ? (-m_run + (far ? btab[512] : 0.f)) : 0.f;
;       {
;         bf16x8 kf[2][NKK];
; #pragma unroll
;         for (int ku = 0; ku < 2; ++ku)
; #pragma unroll
;           for (int kk = 0; kk < NKK; ++kk)
;             kf[ku][kk] = *(const bf16x8*)(Ks + (ku * 32 + ql) * KST + kk * 16 + hh * 8);
;         __builtin_amdgcn_sched_barrier(0);
; #pragma unroll
;         for (int ku = 0; ku < 2; ++ku)
; #pragma unroll
;           for (int r = 0; r < 16; ++r) S[ku][r] = cinit;
; #pragma unroll
;         for (int kk = 0; kk < NKK; ++kk)
; #pragma unroll
;           for (int ku = 0; ku < 2; ++ku)
;             S[ku] = __builtin_amdgcn_mfma_f32_32x32x16_bf16(kf[ku][kk], qf[kk], S[ku], 0, 0, 0);
;       }
.Lmy_w7_dn:
.LBB0_2133:
	s_or_b64 exec, exec, s[14:15]
	s_add_i32 s14, s17, -3
	s_cmp_ge_i32 s14, s16
	s_cbranch_scc1 .LBB0_2126
	v_add_u32_e32 v220, s9, v169
	v_add_u32_e32 v220, 0xfc0000c0, v220
	v_add_u32_e32 v222, s9, v171
	v_mad_i64_i32 v[220:221], s[14:15], v220, s87, v[176:177]
	v_add_u32_e32 v222, 0xfc0000c0, v222
	v_mad_i64_i32 v[222:223], s[14:15], v222, s87, v[178:179]
	v_add_u32_e32 v224, s9, v173
	v_add_u32_e32 v224, 0xfc0000c0, v224
	v_mad_i64_i32 v[224:225], s[14:15], v224, s87, v[180:181]
	v_lshl_add_u64 v[244:245], v[186:187], 0, s[2:3]
	v_add_co_u32_e32 v244, vcc, 0x6000, v244
	s_nop 1
	v_addc_co_u32_e32 v245, vcc, -2, v245, vcc
	v_lshl_add_u64 v[248:249], v[188:189], 0, s[2:3]
	v_add_co_u32_e32 v248, vcc, 0x6000, v248
	s_nop 1
	v_addc_co_u32_e32 v249, vcc, -2, v249, vcc
	s_add_i32 s21, s21, 0xffeffffe
	v_cmp_le_i32_e32 vcc, s21, v197
	s_and_b64 s[14:15], s[12:13], vcc
	v_cmp_ge_u32_e32 vcc, s21, v199
	s_and_b64 s[30:31], s[14:15], vcc
	s_cmp_gt_i32 s17, s16
	s_waitcnt lgkmcnt(0)
	s_barrier
	s_cbranch_scc1 .LBB0_2136
	global_load_dwordx4 v[120:123], v[220:221], off
	global_load_dwordx4 v[124:127], v[222:223], off
	global_load_dwordx4 v[132:135], v[224:225], off
	global_load_dwordx4 v[136:139], v[244:245], off
	global_load_dwordx4 v[140:143], v[248:249], off
.LBB0_2136:
	s_and_saveexec_b64 s[14:15], s[30:31]
	s_cbranch_execz .Lmy_ia1_b
	ds_read_b128 v[2:5], v183 offset:23040
	ds_read_b128 v[6:9], v183 offset:23072
	ds_read_b128 v[10:13], v183 offset:23104
	ds_read_b128 v[144:147], v183 offset:23136
	ds_read_b128 v[148:151], v183 offset:23168
	ds_read_b128 v[152:155], v183 offset:23200
	ds_read_b128 v[156:159], v183 offset:29696
	ds_read_b128 v[160:163], v183 offset:29728
	ds_read_b128 v[204:207], v183 offset:29760
	ds_read_b128 v[208:211], v183 offset:29792
	ds_read_b128 v[212:215], v183 offset:29824
	ds_read_b128 v[216:219], v183 offset:29856
	s_setprio 1
	s_waitcnt lgkmcnt(11)
	v_mfma_f32_32x32x16_bf16 v[64:79], v[2:5], v[84:87], v[228:243]
	v_add_u32_e32 v2, 0x8800, v185
	s_waitcnt lgkmcnt(5)
	v_mfma_f32_32x32x16_bf16 v[48:63], v[156:159], v[84:87], v[228:243]
	s_cmp_gt_i32 s17, s16
	s_cbranch_scc1 .Lmy_w6_nl
	v_add_u32_e32 v226, 0x3400, v182
	s_waitcnt vmcnt(9)
	ds_write_b128 v200, v[104:107]
	s_waitcnt vmcnt(8)
	ds_write_b128 v201, v[108:111]
	s_waitcnt vmcnt(7)
	ds_write_b128 v202, v[112:115]
	s_waitcnt vmcnt(6)
	ds_write2_b64 v226, v[116:117], v[118:119] offset1:1
	v_add_u32_e32 v226, 0x3400, v184
	s_waitcnt vmcnt(5)
	ds_write2_b64 v226, v[128:129], v[130:131] offset1:1
	s_branch .Lmy_w6_dn

; template <int DQK, int MODE> ...
;     ...
;         for (int kk = 0; kk < NKK; ++kk)
; #pragma unroll
;           for (int ku = 0; ku < 2; ++ku)
;             S[ku] = __builtin_amdgcn_mfma_f32_32x32x16_bf16(kf[ku][kk], qf[kk], S[ku], 0, 0, 0);
;       }
;       u32x4 vf[2][4];
;       if (MODE != 2) {
; #pragma unroll
;         for (int du = 0; du < 2; ++du)
; #pragma unroll
;           for (int s4 = 0; s4 < 4; ++s4) {
;             const u16* vp = Vs + (du * 32 + ql) * VST + 16 * s4 + 4 * hh;
;             u32x2 a = *(const u32x2*)vp;
;             u32x2 b = *(const u32x2*)(vp + 8);
;             vf[du][s4] = (u32x4){a.x, a.y, b.x, b.y};
;           }
;         __builtin_amdgcn_sched_barrier(0);
;       }
;       bf16x8 pf[4];
;       if (MODE != 2) {
;         if (MODE == 1 && !far) {
;           const bool noclip = ((qpos0 + 32 * w + 31) - j * 64 <= 256) && ((qpos0 + 32 * w) - (j * 64 + 63) >= -256);
;           if (noclip) {
;             const float* bt = btab + 256 + qpos - j * 64;
; #pragma unroll
;             for (int ku = 0; ku < 2; ++ku)
; #pragma unroll
;               for (int r = 0; r < 16; ++r) S[ku][r] += bt[-(32 * ku + (r & 3) + 8 * (r >> 2) + 4 * hh)];
;           } else {
; #pragma unroll
;             for (int ku = 0; ku < 2; ++ku)
; #pragma unroll
;               for (int r = 0; r < 16; ++r) {
;                 int key = 32 * ku + (r & 3) + 8 * (r >> 2) + 4 * hh;
;                 int rel = qpos - (j * 64 + key);
;                 rel = min(256, max(-256, rel)) + 256;
;                 S[ku][r] += btab[rel];
;               }
;           }
;         }
;         float mx = -1e30f;
; #pragma unroll
;         for (int ku = 0; ku < 2; ++ku)
; #pragma unroll
;           for (int r = 0; r < 16; ++r) mx = fmaxf(mx, S[ku][r]);
;         if (__builtin_amdgcn_ballot_w64(first || mx > 6.f) != 0ull) {
;           mx = xhalf_max(mx);
;           const float d = first ? mx : (mx > 6.f ? mx : 0.f);
;           const float alpha = first ? 1.f : __builtin_amdgcn_exp2f(-d);
;           m_run += d;
;           lsum *= alpha;
; #pragma unroll
;           for (int ku = 0; ku < 2; ++ku)
; #pragma unroll
;             for (int r = 0; r < 16; ++r) S[ku][r] -= d;
; #pragma unroll
;           for (int du = 0; du < 2; ++du)
; #pragma unroll
;             for (int r = 0; r < 16; ++r) O[du][r] *= alpha;
;         }
.Lmy_w6_dn:
	v_mfma_f32_32x32x16_bf16 v[64:79], v[6:9], v[80:83], v[64:79]
	s_waitcnt lgkmcnt(9)
	v_mfma_f32_32x32x16_bf16 v[48:63], v[160:163], v[80:83], v[48:63]
	ds_read2_b64 v[160:163], v2 offset0:192 offset1:194
	v_mfma_f32_32x32x16_bf16 v[64:79], v[10:13], v[92:95], v[64:79]
	s_waitcnt lgkmcnt(9)
	v_mfma_f32_32x32x16_bf16 v[48:63], v[204:207], v[92:95], v[48:63]
	v_mfma_f32_32x32x16_bf16 v[64:79], v[144:147], v[88:91], v[64:79]
	s_waitcnt lgkmcnt(8)
	v_mfma_f32_32x32x16_bf16 v[48:63], v[208:211], v[88:91], v[48:63]
	v_mfma_f32_32x32x16_bf16 v[64:79], v[148:151], v[100:103], v[64:79]
	s_waitcnt lgkmcnt(7)
	v_mfma_f32_32x32x16_bf16 v[48:63], v[212:215], v[100:103], v[48:63]
	v_mfma_f32_32x32x16_bf16 v[64:79], v[152:155], v[96:99], v[64:79]
	ds_read2_b64 v[152:155], v2 offset0:196 offset1:198
	ds_read2_b64 v[144:147], v2 offset0:200 offset1:202
	ds_read2_b64 v[6:9], v2 offset0:204 offset1:206
	v_add_u32_e32 v2, 0xa000, v185
	ds_read2_b64 v[156:159], v2 offset0:32 offset1:34
	ds_read2_b64 v[148:151], v2 offset0:36 offset1:38
	ds_read2_b64 v[10:13], v2 offset0:40 offset1:42
	ds_read2_b64 v[2:5], v2 offset0:44 offset1:46
	s_waitcnt lgkmcnt(13)
	v_mfma_f32_32x32x16_bf16 v[48:63], v[216:219], v[96:99], v[48:63]
	s_setprio 0
	s_nop 1
	v_max3_f32 v14, v64, s96, v65
	v_max3_f32 v14, v14, v66, v67
	v_max3_f32 v14, v14, v68, v69
	v_max3_f32 v14, v14, v70, v71
	v_max3_f32 v14, v14, v72, v73
	v_max3_f32 v14, v14, v74, v75
	v_max3_f32 v14, v14, v76, v77
	v_max3_f32 v14, v14, v78, v79
	s_nop 1
	v_max3_f32 v14, v14, v48, v49
	v_max3_f32 v14, v14, v50, v51
	v_max3_f32 v14, v14, v52, v53
	v_max3_f32 v14, v14, v54, v55
	v_max3_f32 v14, v14, v56, v57
	v_max3_f32 v14, v14, v58, v59
	v_max3_f32 v14, v14, v60, v61
	v_max3_f32 v14, v14, v62, v63
	v_cmp_lt_f32_e32 vcc, s97, v14
	s_or_b64 vcc, s[10:11], vcc
	s_cbranch_vccz .LBB0_2124
	v_mov_b32_e32 v15, v14
	s_nop 1
	v_permlane32_swap_b32_e32 v14, v15
	v_max_f32_e32 v15, v15, v15
	v_max_f32_e32 v14, v14, v14
	v_max_f32_e32 v14, v14, v15
	v_cmp_lt_f32_e32 vcc, s97, v14
	s_or_b64 vcc, s[10:11], vcc
	s_nop 0
	v_cndmask_b32_e32 v14, 0, v14, vcc
	v_exp_f32_e64 v15, -v14
	v_add_f32_e32 v0, v0, v14
	v_sub_f32_e32 v228, 0, v0
	v_mov_b32_e32 v229, v228
	v_mov_b32_e32 v230, v228
	v_mov_b32_e32 v231, v228
	v_mov_b32_e32 v232, v228
	v_mov_b32_e32 v233, v228
	v_mov_b32_e32 v234, v228
	v_mov_b32_e32 v235, v228
	v_mov_b32_e32 v236, v228
	v_mov_b32_e32 v237, v228
	v_mov_b32_e32 v238, v228
	v_mov_b32_e32 v239, v228
	v_mov_b32_e32 v240, v228
	v_mov_b32_e32 v241, v228
	v_mov_b32_e32 v242, v228
	v_mov_b32_e32 v243, v228
	v_cndmask_b32_e64 v204, v15, 1.0, s[10:11]
	v_mul_f32_e32 v175, v175, v204
	v_pk_add_f32 v[64:65], v[64:65], v[14:15] op_sel_hi:[1,0] neg_lo:[0,1] neg_hi:[0,1]
	v_pk_add_f32 v[66:67], v[66:67], v[14:15] op_sel_hi:[1,0] neg_lo:[0,1] neg_hi:[0,1]
	v_pk_add_f32 v[68:69], v[68:69], v[14:15] op_sel_hi:[1,0] neg_lo:[0,1] neg_hi:[0,1]
	v_pk_add_f32 v[70:71], v[70:71], v[14:15] op_sel_hi:[1,0] neg_lo:[0,1] neg_hi:[0,1]
	v_pk_add_f32 v[72:73], v[72:73], v[14:15] op_sel_hi:[1,0] neg_lo:[0,1] neg_hi:[0,1]
	v_pk_add_f32 v[74:75], v[74:75], v[14:15] op_sel_hi:[1,0] neg_lo:[0,1] neg_hi:[0,1]
	v_pk_add_f32 v[76:77], v[76:77], v[14:15] op_sel_hi:[1,0] neg_lo:[0,1] neg_hi:[0,1]
	v_pk_add_f32 v[78:79], v[78:79], v[14:15] op_sel_hi:[1,0] neg_lo:[0,1] neg_hi:[0,1]
	v_pk_add_f32 v[48:49], v[48:49], v[14:15] op_sel_hi:[1,0] neg_lo:[0,1] neg_hi:[0,1]
	v_pk_add_f32 v[50:51], v[50:51], v[14:15] op_sel_hi:[1,0] neg_lo:[0,1] neg_hi:[0,1]
	v_pk_add_f32 v[52:53], v[52:53], v[14:15] op_sel_hi:[1,0] neg_lo:[0,1] neg_hi:[0,1]
	v_pk_add_f32 v[54:55], v[54:55], v[14:15] op_sel_hi:[1,0] neg_lo:[0,1] neg_hi:[0,1]
	v_pk_add_f32 v[56:57], v[56:57], v[14:15] op_sel_hi:[1,0] neg_lo:[0,1] neg_hi:[0,1]
	v_pk_add_f32 v[58:59], v[58:59], v[14:15] op_sel_hi:[1,0] neg_lo:[0,1] neg_hi:[0,1]
	v_pk_add_f32 v[60:61], v[60:61], v[14:15] op_sel_hi:[1,0] neg_lo:[0,1] neg_hi:[0,1]
	v_pk_add_f32 v[62:63], v[62:63], v[14:15] op_sel_hi:[1,0] neg_lo:[0,1] neg_hi:[0,1]
	v_pk_mul_f32 v[46:47], v[46:47], v[204:205] op_sel_hi:[1,0]
	v_pk_mul_f32 v[44:45], v[44:45], v[204:205] op_sel_hi:[1,0]
	v_pk_mul_f32 v[42:43], v[42:43], v[204:205] op_sel_hi:[1,0]
	v_pk_mul_f32 v[40:41], v[40:41], v[204:205] op_sel_hi:[1,0]
	v_pk_mul_f32 v[38:39], v[38:39], v[204:205] op_sel_hi:[1,0]
	v_pk_mul_f32 v[36:37], v[36:37], v[204:205] op_sel_hi:[1,0]
	v_pk_mul_f32 v[34:35], v[34:35], v[204:205] op_sel_hi:[1,0]
	v_pk_mul_f32 v[32:33], v[32:33], v[204:205] op_sel_hi:[1,0]
	v_pk_mul_f32 v[30:31], v[30:31], v[204:205] op_sel_hi:[1,0]
	v_pk_mul_f32 v[28:29], v[28:29], v[204:205] op_sel_hi:[1,0]
	v_pk_mul_f32 v[26:27], v[26:27], v[204:205] op_sel_hi:[1,0]
	v_pk_mul_f32 v[24:25], v[24:25], v[204:205] op_sel_hi:[1,0]
	v_pk_mul_f32 v[22:23], v[22:23], v[204:205] op_sel_hi:[1,0]
	v_pk_mul_f32 v[20:21], v[20:21], v[204:205] op_sel_hi:[1,0]
	v_pk_mul_f32 v[18:19], v[18:19], v[204:205] op_sel_hi:[1,0]
	v_pk_mul_f32 v[16:17], v[16:17], v[204:205] op_sel_hi:[1,0]
	s_branch .LBB0_2124
